# MLA context-item epilogue: og stores paired into dwordx4 like the latent epilogue
# baseline (speedup 1.0000x reference)
.LBB0_527:
	s_or_b64 exec, exec, s[8:9]
	s_nop 0
	v_rcp_f32_e32 v67, v96
	s_lshl_b64 s[6:7], s[6:7], 12
	s_add_u32 s6, s23, s6
	s_addc_u32 s7, s24, s7
	v_mul_f32_e32 v0, v67, v0
	v_mul_f32_e32 v1, v67, v1
	v_cvt_pk_bf16_f32 v80, v0, v1
	v_mul_f32_e32 v0, v67, v2
	v_mul_f32_e32 v1, v67, v3
	v_cvt_pk_bf16_f32 v81, v0, v1
	v_mul_f32_e32 v0, v67, v4
	v_mul_f32_e32 v1, v67, v5
	v_cvt_pk_bf16_f32 v82, v0, v1
	v_mul_f32_e32 v0, v67, v6
	v_mul_f32_e32 v1, v67, v7
	v_cvt_pk_bf16_f32 v83, v0, v1
	v_mul_f32_e32 v0, v67, v8
	v_mul_f32_e32 v1, v67, v9
	v_cvt_pk_bf16_f32 v84, v0, v1
	v_mul_f32_e32 v0, v67, v10
	v_mul_f32_e32 v1, v67, v11
	v_cvt_pk_bf16_f32 v85, v0, v1
	v_mul_f32_e32 v0, v67, v12
	v_mul_f32_e32 v1, v67, v13
	v_cvt_pk_bf16_f32 v86, v0, v1
	v_mul_f32_e32 v0, v67, v14
	v_mul_f32_e32 v1, v67, v15
	v_cvt_pk_bf16_f32 v87, v0, v1
	v_mul_f32_e32 v0, v67, v16
	v_mul_f32_e32 v1, v67, v17
	v_cvt_pk_bf16_f32 v88, v0, v1
	v_mul_f32_e32 v0, v67, v18
	v_mul_f32_e32 v1, v67, v19
	v_cvt_pk_bf16_f32 v89, v0, v1
	v_mul_f32_e32 v0, v67, v20
	v_mul_f32_e32 v1, v67, v21
	v_cvt_pk_bf16_f32 v90, v0, v1
	v_mul_f32_e32 v0, v67, v22
	v_mul_f32_e32 v1, v67, v23
	v_cvt_pk_bf16_f32 v91, v0, v1
	v_mul_f32_e32 v0, v67, v24
	v_mul_f32_e32 v1, v67, v25
	v_cvt_pk_bf16_f32 v92, v0, v1
	v_mul_f32_e32 v0, v67, v26
	v_mul_f32_e32 v1, v67, v27
	v_cvt_pk_bf16_f32 v93, v0, v1
	v_mul_f32_e32 v0, v67, v28
	v_mul_f32_e32 v1, v67, v29
	v_cvt_pk_bf16_f32 v94, v0, v1
	v_mul_f32_e32 v0, v67, v30
	v_mul_f32_e32 v1, v67, v31
	v_cvt_pk_bf16_f32 v95, v0, v1
	v_mul_f32_e32 v0, v67, v32
	v_mul_f32_e32 v1, v67, v33
	v_cvt_pk_bf16_f32 v76, v0, v1
	v_mul_f32_e32 v0, v67, v34
	v_mul_f32_e32 v1, v67, v35
	v_cvt_pk_bf16_f32 v77, v0, v1
	v_mul_f32_e32 v0, v67, v36
	v_mul_f32_e32 v1, v67, v37
	v_cvt_pk_bf16_f32 v78, v0, v1
	v_mul_f32_e32 v0, v67, v38
	v_mul_f32_e32 v1, v67, v39
	v_cvt_pk_bf16_f32 v79, v0, v1
	v_mul_f32_e32 v0, v67, v40
	v_mul_f32_e32 v1, v67, v41
	v_cvt_pk_bf16_f32 v72, v0, v1
	v_mul_f32_e32 v0, v67, v42
	v_mul_f32_e32 v1, v67, v43
	v_cvt_pk_bf16_f32 v73, v0, v1
	v_mul_f32_e32 v0, v67, v44
	v_mul_f32_e32 v1, v67, v45
	v_cvt_pk_bf16_f32 v74, v0, v1
	v_mul_f32_e32 v0, v67, v46
	v_mul_f32_e32 v1, v67, v47
	v_cvt_pk_bf16_f32 v75, v0, v1
	v_mul_f32_e32 v0, v67, v48
	v_mul_f32_e32 v1, v67, v49
	v_cvt_pk_bf16_f32 v68, v0, v1
	v_mul_f32_e32 v0, v67, v50
	v_mul_f32_e32 v1, v67, v51
	v_cvt_pk_bf16_f32 v69, v0, v1
	v_mul_f32_e32 v0, v67, v52
	v_mul_f32_e32 v1, v67, v53
	v_cvt_pk_bf16_f32 v70, v0, v1
	v_mul_f32_e32 v0, v67, v54
	v_mul_f32_e32 v1, v67, v55
	s_lshl_b32 s8, s0, 8
	v_cvt_pk_bf16_f32 v71, v0, v1
	v_mul_f32_e32 v0, v67, v56
	v_mul_f32_e32 v1, v67, v57
	s_add_u32 s6, s6, s8
	v_cvt_pk_bf16_f32 v64, v0, v1
	v_mul_f32_e32 v0, v67, v58
	v_mul_f32_e32 v1, v67, v59
	s_addc_u32 s7, s7, 0
	v_lshl_add_u64 v[150:151], s[6:7], 0, v[200:201]
	v_lshl_add_u64 v[150:151], v[150:151], 0, v[196:197]
	global_load_dwordx2 v[152:153], v[150:151], off offset:32
	global_load_dwordx2 v[154:155], v[150:151], off offset:48
	global_load_dwordx2 v[156:157], v[150:151], off offset:64
	global_load_dwordx2 v[158:159], v[150:151], off offset:80
	global_load_dwordx2 v[160:161], v[150:151], off offset:96
	global_load_dwordx2 v[162:163], v[150:151], off offset:112
	global_load_dwordx2 v[164:165], v[150:151], off offset:128
	global_load_dwordx2 v[166:167], v[150:151], off offset:144
	global_load_dwordx2 v[168:169], v[150:151], off offset:160
	global_load_dwordx2 v[170:171], v[150:151], off offset:176
	global_load_dwordx2 v[172:173], v[150:151], off offset:192
	global_load_dwordx2 v[174:175], v[150:151], off offset:208
	global_load_dwordx2 v[176:177], v[150:151], off offset:224
	global_load_dwordx2 v[178:179], v[150:151], off offset:240
	global_load_dwordx2 v[150:151], v[150:151], off offset:16
	v_cvt_pk_bf16_f32 v65, v0, v1
	v_mul_f32_e32 v0, v67, v60
	v_mul_f32_e32 v1, v67, v61
	s_lshl_b32 s0, s0, 15
	v_cvt_pk_bf16_f32 v66, v0, v1
	v_mul_f32_e32 v0, v67, v62
	v_mul_f32_e32 v1, v67, v63
	v_lshl_add_u64 v[62:63], v[198:199], 0, s[0:1]
	v_cvt_pk_bf16_f32 v67, v0, v1
	global_load_dwordx2 v[0:1], v[62:63], off
	global_load_dwordx2 v[2:3], v[62:63], off offset:16
	global_load_dwordx2 v[16:17], v[62:63], off offset:32
	global_load_dwordx2 v[18:19], v[62:63], off offset:48
	global_load_dwordx2 v[20:21], v[62:63], off offset:64
	global_load_dwordx2 v[22:23], v[62:63], off offset:80
	global_load_dwordx2 v[24:25], v[62:63], off offset:96
	global_load_dwordx2 v[26:27], v[62:63], off offset:112
	global_load_dwordx2 v[28:29], v[62:63], off offset:128
	global_load_dwordx2 v[30:31], v[62:63], off offset:144
	v_add_co_u32_e32 v48, vcc, s27, v62
	s_add_i32 s20, s20, s60
	s_waitcnt vmcnt(0)
	v_mfma_f32_32x32x16_bf16 v[0:15], v[0:3], v[80:83], 0
	v_addc_co_u32_e32 v49, vcc, 0, v63, vcc
	v_add_co_u32_e32 v138, vcc, s17, v62
	s_cmpk_lt_i32 s20, 0x200
	s_nop 0
	v_addc_co_u32_e32 v139, vcc, 0, v63, vcc
	v_mfma_f32_32x32x16_bf16 v[0:15], v[16:19], v[84:87], v[0:15]
	global_load_dwordx2 v[16:17], v[62:63], off offset:160
	global_load_dwordx2 v[18:19], v[62:63], off offset:176
	v_add_co_u32_e32 v146, vcc, s28, v62
	s_nop 1
	v_addc_co_u32_e32 v147, vcc, 0, v63, vcc
	v_mfma_f32_32x32x16_bf16 v[0:15], v[20:23], v[88:91], v[0:15]
	global_load_dwordx2 v[20:21], v[48:49], off
	global_load_dwordx2 v[22:23], v[48:49], off offset:16
	global_load_dwordx2 v[32:33], v[62:63], off offset:192
	global_load_dwordx2 v[34:35], v[62:63], off offset:208
	global_load_dwordx2 v[36:37], v[62:63], off offset:224
	global_load_dwordx2 v[38:39], v[62:63], off offset:240
	global_load_dwordx2 v[40:41], v[48:49], off offset:32
	global_load_dwordx2 v[42:43], v[48:49], off offset:48
	global_load_dwordx2 v[44:45], v[48:49], off offset:64
	global_load_dwordx2 v[46:47], v[48:49], off offset:80
	v_lshl_add_u64 v[62:63], s[6:7], 0, v[200:201]
	v_lshl_add_u64 v[96:97], v[62:63], 0, v[196:197]
	v_bfe_u32 v180, v192, 5, 1
	v_lshlrev_b32_e32 v180, 3, v180
	v_mov_b32_e32 v181, 0
	v_lshl_add_u64 v[180:181], v[96:97], 0, v[180:181]
	v_mfma_f32_32x32x16_bf16 v[0:15], v[24:27], v[92:95], v[0:15]
	v_mfma_f32_32x32x16_bf16 v[0:15], v[28:31], v[76:79], v[0:15]
	s_waitcnt vmcnt(0)
	v_mfma_f32_32x32x16_bf16 v[0:15], v[16:19], v[72:75], v[0:15]
	v_mfma_f32_32x32x16_bf16 v[0:15], v[32:35], v[68:71], v[0:15]
	global_load_dwordx2 v[32:33], v[48:49], off offset:96
	global_load_dwordx2 v[34:35], v[48:49], off offset:112
	v_mfma_f32_32x32x16_bf16 v[0:15], v[36:39], v[64:67], v[0:15]
	global_load_dwordx2 v[36:37], v[138:139], off
	global_load_dwordx2 v[38:39], v[138:139], off offset:16
	global_load_dwordx2 v[50:51], v[138:139], off offset:32
	global_load_dwordx2 v[52:53], v[138:139], off offset:48
	global_load_dwordx2 v[54:55], v[138:139], off offset:64
	global_load_dwordx2 v[56:57], v[138:139], off offset:80
	global_load_dwordx2 v[58:59], v[138:139], off offset:96
	global_load_dwordx2 v[60:61], v[138:139], off offset:112
	global_load_dwordx2 v[98:99], v[146:147], off
	global_load_dwordx2 v[100:101], v[146:147], off offset:16
	global_load_dwordx2 v[102:103], v[146:147], off offset:32
	global_load_dwordx2 v[104:105], v[146:147], off offset:48
	global_load_dwordx2 v[106:107], v[146:147], off offset:64
	global_load_dwordx2 v[108:109], v[146:147], off offset:80
	global_load_dwordx2 v[148:149], v[96:97], off
	v_mfma_f32_32x32x16_bf16 v[16:31], v[20:23], v[80:83], 0
	global_load_dwordx2 v[110:111], v[146:147], off offset:96
	global_load_dwordx2 v[112:113], v[146:147], off offset:112
	global_load_dwordx2 v[114:115], v[48:49], off offset:128
	global_load_dwordx2 v[116:117], v[48:49], off offset:144
	global_load_dwordx2 v[118:119], v[48:49], off offset:160
	global_load_dwordx2 v[120:121], v[48:49], off offset:176
	global_load_dwordx2 v[122:123], v[48:49], off offset:192
	global_load_dwordx2 v[124:125], v[48:49], off offset:208
	global_load_dwordx2 v[126:127], v[48:49], off offset:224
	global_load_dwordx2 v[128:129], v[48:49], off offset:240
	global_load_dwordx2 v[130:131], v[138:139], off offset:128
	global_load_dwordx2 v[132:133], v[138:139], off offset:144
	global_load_dwordx2 v[134:135], v[138:139], off offset:160
	global_load_dwordx2 v[136:137], v[138:139], off offset:176
	v_mfma_f32_32x32x16_bf16 v[16:31], v[40:43], v[84:87], v[16:31]
	v_mfma_f32_32x32x16_bf16 v[16:31], v[44:47], v[88:91], v[16:31]
	s_waitcnt vmcnt(0)
	v_mfma_f32_32x32x16_bf16 v[16:31], v[32:35], v[92:95], v[16:31]
	v_mfma_f32_32x32x16_bf16 v[32:47], v[36:39], v[80:83], 0
	v_mfma_f32_32x32x16_bf16 v[32:47], v[50:53], v[84:87], v[32:47]
	v_mfma_f32_32x32x16_bf16 v[32:47], v[54:57], v[88:91], v[32:47]
	v_mfma_f32_32x32x16_bf16 v[32:47], v[58:61], v[92:95], v[32:47]
	v_mfma_f32_32x32x16_bf16 v[48:63], v[98:101], v[80:83], 0
	global_load_dwordx2 v[80:81], v[138:139], off offset:192
	global_load_dwordx2 v[82:83], v[138:139], off offset:208
	global_load_dwordx2 v[98:99], v[138:139], off offset:224
	global_load_dwordx2 v[100:101], v[138:139], off offset:240
	s_nop 0
	global_load_dwordx2 v[138:139], v[146:147], off offset:128
	global_load_dwordx2 v[140:141], v[146:147], off offset:144
	global_load_dwordx2 v[142:143], v[146:147], off offset:160
	global_load_dwordx2 v[144:145], v[146:147], off offset:176
	v_mfma_f32_32x32x16_bf16 v[48:63], v[102:105], v[84:87], v[48:63]
	global_load_dwordx2 v[84:85], v[146:147], off offset:192
	global_load_dwordx2 v[86:87], v[146:147], off offset:208
	global_load_dwordx2 v[102:103], v[146:147], off offset:224
	global_load_dwordx2 v[104:105], v[146:147], off offset:240
	v_lshlrev_b32_e32 v146, 16, v148
	v_and_b32_e32 v147, 0xffff0000, v148
	v_lshlrev_b32_e32 v148, 16, v149
	v_mul_f32_e32 v0, v0, v146
	v_mul_f32_e32 v1, v1, v147
	v_cvt_pk_bf16_f32 v0, v0, v1
	v_mfma_f32_32x32x16_bf16 v[48:63], v[106:109], v[88:91], v[48:63]
	v_and_b32_e32 v88, 0xffff0000, v149
	v_mul_f32_e32 v1, v2, v148
	v_mul_f32_e32 v2, v3, v88
	v_cvt_pk_bf16_f32 v1, v1, v2
	s_nop 0
	v_mov_b32_e32 v184, v0
	v_mov_b32_e32 v185, v1
	v_mfma_f32_32x32x16_bf16 v[16:31], v[114:117], v[76:79], v[16:31]
	s_waitcnt vmcnt(0)
	v_lshlrev_b32_e32 v0, 16, v150
	v_and_b32_e32 v1, 0xffff0000, v150
	v_lshlrev_b32_e32 v2, 16, v151
	v_and_b32_e32 v3, 0xffff0000, v151
	v_mul_f32_e32 v0, v4, v0
	v_mul_f32_e32 v1, v5, v1
	v_mul_f32_e32 v2, v6, v2
	v_mul_f32_e32 v3, v7, v3
	v_cvt_pk_bf16_f32 v0, v0, v1
	v_cvt_pk_bf16_f32 v1, v2, v3
	v_mfma_f32_32x32x16_bf16 v[16:31], v[118:121], v[72:75], v[16:31]
	v_mov_b32_e32 v186, v0
	v_mov_b32_e32 v187, v1
	s_nop 1
	v_permlane32_swap_b32_e32 v184, v186
	v_permlane32_swap_b32_e32 v185, v187
	global_store_dwordx4 v[180:181], v[184:187], off
	v_lshlrev_b32_e32 v0, 16, v152
	v_and_b32_e32 v1, 0xffff0000, v152
	v_lshlrev_b32_e32 v2, 16, v153
	v_and_b32_e32 v3, 0xffff0000, v153
	v_mul_f32_e32 v0, v8, v0
	v_mul_f32_e32 v1, v9, v1
	v_mul_f32_e32 v2, v10, v2
	v_mul_f32_e32 v3, v11, v3
	v_cvt_pk_bf16_f32 v0, v0, v1
	v_cvt_pk_bf16_f32 v1, v2, v3
	v_mfma_f32_32x32x16_bf16 v[16:31], v[122:125], v[68:71], v[16:31]
	v_mov_b32_e32 v184, v0
	v_mov_b32_e32 v185, v1
	v_lshlrev_b32_e32 v0, 16, v154
	v_and_b32_e32 v1, 0xffff0000, v154
	v_lshlrev_b32_e32 v2, 16, v155
	v_and_b32_e32 v3, 0xffff0000, v155
	v_mul_f32_e32 v0, v12, v0
	v_mul_f32_e32 v1, v13, v1
	v_mul_f32_e32 v2, v14, v2
	v_mul_f32_e32 v3, v15, v3
	v_cvt_pk_bf16_f32 v0, v0, v1
	v_cvt_pk_bf16_f32 v1, v2, v3
	v_mfma_f32_32x32x16_bf16 v[16:31], v[126:129], v[64:67], v[16:31]
	v_mov_b32_e32 v186, v0
	v_mov_b32_e32 v187, v1
	s_nop 1
	v_permlane32_swap_b32_e32 v184, v186
	v_permlane32_swap_b32_e32 v185, v187
	global_store_dwordx4 v[180:181], v[184:187], off offset:32
	v_lshlrev_b32_e32 v0, 16, v156
	v_and_b32_e32 v1, 0xffff0000, v156
	v_lshlrev_b32_e32 v2, 16, v157
	v_and_b32_e32 v3, 0xffff0000, v157
	s_nop 5
	v_mul_f32_e32 v0, v16, v0
	v_mul_f32_e32 v1, v17, v1
	v_mul_f32_e32 v2, v18, v2
	v_mul_f32_e32 v3, v19, v3
	v_cvt_pk_bf16_f32 v0, v0, v1
	v_cvt_pk_bf16_f32 v1, v2, v3
	v_mfma_f32_32x32x16_bf16 v[32:47], v[130:133], v[76:79], v[32:47]
	v_mov_b32_e32 v184, v0
	v_mov_b32_e32 v185, v1
	v_lshlrev_b32_e32 v0, 16, v158
	v_and_b32_e32 v1, 0xffff0000, v158
	v_lshlrev_b32_e32 v2, 16, v159
	v_and_b32_e32 v3, 0xffff0000, v159
	v_mul_f32_e32 v0, v20, v0
	v_mul_f32_e32 v1, v21, v1
	v_mul_f32_e32 v2, v22, v2
	v_mul_f32_e32 v3, v23, v3
	v_cvt_pk_bf16_f32 v0, v0, v1
	v_cvt_pk_bf16_f32 v1, v2, v3
	v_mfma_f32_32x32x16_bf16 v[32:47], v[134:137], v[72:75], v[32:47]
	v_mov_b32_e32 v186, v0
	v_mov_b32_e32 v187, v1
	s_nop 1
	v_permlane32_swap_b32_e32 v184, v186
	v_permlane32_swap_b32_e32 v185, v187
	global_store_dwordx4 v[180:181], v[184:187], off offset:64
	v_lshlrev_b32_e32 v0, 16, v160
	v_and_b32_e32 v1, 0xffff0000, v160
	v_lshlrev_b32_e32 v2, 16, v161
	v_and_b32_e32 v3, 0xffff0000, v161
	v_mul_f32_e32 v0, v24, v0
	v_mul_f32_e32 v1, v25, v1
	v_mul_f32_e32 v2, v26, v2
	v_mul_f32_e32 v3, v27, v3
	v_cvt_pk_bf16_f32 v0, v0, v1
	v_cvt_pk_bf16_f32 v1, v2, v3
	v_mfma_f32_32x32x16_bf16 v[32:47], v[80:83], v[68:71], v[32:47]
	v_mov_b32_e32 v184, v0
	v_mov_b32_e32 v185, v1
	v_lshlrev_b32_e32 v0, 16, v162
	v_and_b32_e32 v1, 0xffff0000, v162
	v_lshlrev_b32_e32 v2, 16, v163
	v_and_b32_e32 v3, 0xffff0000, v163
	v_mul_f32_e32 v0, v28, v0
	v_mul_f32_e32 v1, v29, v1
	v_mul_f32_e32 v2, v30, v2
	v_mul_f32_e32 v3, v31, v3
	v_cvt_pk_bf16_f32 v0, v0, v1
	v_cvt_pk_bf16_f32 v1, v2, v3
	v_mfma_f32_32x32x16_bf16 v[32:47], v[98:101], v[64:67], v[32:47]
	v_mov_b32_e32 v186, v0
	v_mov_b32_e32 v187, v1
	s_nop 1
	v_permlane32_swap_b32_e32 v184, v186
	v_permlane32_swap_b32_e32 v185, v187
	global_store_dwordx4 v[180:181], v[184:187], off offset:96
	v_lshlrev_b32_e32 v0, 16, v164
	v_and_b32_e32 v1, 0xffff0000, v164
	v_lshlrev_b32_e32 v2, 16, v165
	v_and_b32_e32 v3, 0xffff0000, v165
	s_nop 5
	v_mul_f32_e32 v0, v32, v0
	v_mul_f32_e32 v1, v33, v1
	v_mul_f32_e32 v2, v34, v2
	v_mul_f32_e32 v3, v35, v3
	v_cvt_pk_bf16_f32 v0, v0, v1
	v_cvt_pk_bf16_f32 v1, v2, v3
	v_mfma_f32_32x32x16_bf16 v[48:63], v[110:113], v[92:95], v[48:63]
	v_mov_b32_e32 v184, v0
	v_mov_b32_e32 v185, v1
	v_lshlrev_b32_e32 v0, 16, v166
	v_and_b32_e32 v1, 0xffff0000, v166
	v_lshlrev_b32_e32 v2, 16, v167
	v_and_b32_e32 v3, 0xffff0000, v167
	v_mul_f32_e32 v0, v36, v0
	v_mul_f32_e32 v1, v37, v1
	v_mul_f32_e32 v2, v38, v2
	v_mul_f32_e32 v3, v39, v3
	v_cvt_pk_bf16_f32 v0, v0, v1
	v_cvt_pk_bf16_f32 v1, v2, v3
	v_mfma_f32_32x32x16_bf16 v[48:63], v[138:141], v[76:79], v[48:63]
	v_mov_b32_e32 v186, v0
	v_mov_b32_e32 v187, v1
	s_nop 1
	v_permlane32_swap_b32_e32 v184, v186
	v_permlane32_swap_b32_e32 v185, v187
	global_store_dwordx4 v[180:181], v[184:187], off offset:128
	v_lshlrev_b32_e32 v0, 16, v168
	v_and_b32_e32 v1, 0xffff0000, v168
	v_lshlrev_b32_e32 v2, 16, v169
	v_and_b32_e32 v3, 0xffff0000, v169
	v_mul_f32_e32 v0, v40, v0
	v_mul_f32_e32 v1, v41, v1
	v_mul_f32_e32 v2, v42, v2
	v_mul_f32_e32 v3, v43, v3
	v_cvt_pk_bf16_f32 v0, v0, v1
	v_cvt_pk_bf16_f32 v1, v2, v3
	v_mfma_f32_32x32x16_bf16 v[48:63], v[142:145], v[72:75], v[48:63]
	v_mov_b32_e32 v184, v0
	v_mov_b32_e32 v185, v1
	v_lshlrev_b32_e32 v0, 16, v170
	v_and_b32_e32 v1, 0xffff0000, v170
	v_lshlrev_b32_e32 v2, 16, v171
	v_and_b32_e32 v3, 0xffff0000, v171
	v_mul_f32_e32 v0, v44, v0
	v_mul_f32_e32 v1, v45, v1
	v_mul_f32_e32 v2, v46, v2
	v_mul_f32_e32 v3, v47, v3
	v_cvt_pk_bf16_f32 v0, v0, v1
	v_cvt_pk_bf16_f32 v1, v2, v3
	v_mfma_f32_32x32x16_bf16 v[48:63], v[84:87], v[68:71], v[48:63]
	v_mov_b32_e32 v186, v0
	v_mov_b32_e32 v187, v1
	s_nop 1
	v_permlane32_swap_b32_e32 v184, v186
	v_permlane32_swap_b32_e32 v185, v187
	global_store_dwordx4 v[180:181], v[184:187], off offset:160
	v_lshlrev_b32_e32 v0, 16, v172
	v_mfma_f32_32x32x16_bf16 v[48:63], v[102:105], v[64:67], v[48:63]
	v_and_b32_e32 v1, 0xffff0000, v172
	v_lshlrev_b32_e32 v2, 16, v173
	v_and_b32_e32 v3, 0xffff0000, v173
	s_nop 8
	v_mul_f32_e32 v0, v48, v0
	v_mul_f32_e32 v1, v49, v1
	v_mul_f32_e32 v2, v50, v2
	v_mul_f32_e32 v3, v51, v3
	v_cvt_pk_bf16_f32 v0, v0, v1
	v_cvt_pk_bf16_f32 v1, v2, v3
	s_nop 0
	v_mov_b32_e32 v184, v0
	v_mov_b32_e32 v185, v1
	v_lshlrev_b32_e32 v0, 16, v174
	v_and_b32_e32 v1, 0xffff0000, v174
	v_lshlrev_b32_e32 v2, 16, v175
	v_and_b32_e32 v3, 0xffff0000, v175
	v_mul_f32_e32 v0, v52, v0
	v_mul_f32_e32 v1, v53, v1
	v_mul_f32_e32 v2, v54, v2
	v_mul_f32_e32 v3, v55, v3
	v_cvt_pk_bf16_f32 v0, v0, v1
	v_cvt_pk_bf16_f32 v1, v2, v3
	s_nop 0
	v_mov_b32_e32 v186, v0
	v_mov_b32_e32 v187, v1
	s_nop 1
	v_permlane32_swap_b32_e32 v184, v186
	v_permlane32_swap_b32_e32 v185, v187
	global_store_dwordx4 v[180:181], v[184:187], off offset:192
	v_lshlrev_b32_e32 v0, 16, v176
	v_and_b32_e32 v1, 0xffff0000, v176
	v_lshlrev_b32_e32 v2, 16, v177
	v_and_b32_e32 v3, 0xffff0000, v177
	v_mul_f32_e32 v0, v56, v0
	v_mul_f32_e32 v1, v57, v1
	v_mul_f32_e32 v2, v58, v2
	v_mul_f32_e32 v3, v59, v3
	v_cvt_pk_bf16_f32 v0, v0, v1
	v_cvt_pk_bf16_f32 v1, v2, v3
	s_nop 0
	v_mov_b32_e32 v184, v0
	v_mov_b32_e32 v185, v1
	v_lshlrev_b32_e32 v0, 16, v178
	v_and_b32_e32 v1, 0xffff0000, v178
	v_lshlrev_b32_e32 v2, 16, v179
	v_and_b32_e32 v3, 0xffff0000, v179
	v_mul_f32_e32 v0, v60, v0
	v_mul_f32_e32 v1, v61, v1
	v_mul_f32_e32 v2, v62, v2
	v_mul_f32_e32 v3, v63, v3
	v_cvt_pk_bf16_f32 v0, v0, v1
	v_cvt_pk_bf16_f32 v1, v2, v3
	v_mov_b32_e32 v186, v0
	v_mov_b32_e32 v187, v1
	s_nop 1
	v_permlane32_swap_b32_e32 v184, v186
	v_permlane32_swap_b32_e32 v185, v187
	global_store_dwordx4 v[180:181], v[184:187], off offset:224
	s_waitcnt lgkmcnt(0)
	s_barrier
	s_cbranch_scc0 .LBB0_548
